# ou3 + gemm2 dynamic tile assignment (per-XCD atomic tile counter) - paired timing of v174
# speedup vs baseline: 1.0102x; 1.0102x over previous
; DI int otid() { int t = __builtin_amdgcn_workitem_id_x(); asm volatile("" : "+v"(t)); return t; }
;     ...
;       __syncthreads();
;       if (tid == 0) *(int*)(smem + SLOT) = 64 + (int)atomicAdd(&p.ctr[l + ci], 1u);
;       __syncthreads();
;       id = *(const int*)(smem + SLOT);
; DI void gemm2_phase(const Params& p, int l, char* smem, const bool dry = false) {
;   bf16_t* sm = (bf16_t*)smem;
;   const int tid = otid(), lane = tid & 63, wave = tid >> 6;
;   const int wm = wave >> 1, wn = wave & 1, g4 = lane >> 4, cl = lane & 15;
;   const int slots = gridDim.x >> 3, slot = blockIdx.x >> 3;
;   for (int e = slot;; e += slots) {
;     int mt, nt;
;     if (!xcd_tile(e, 36, mt, nt)) break;
.LBB0_1697:
	s_or_b64 exec, exec, s[4:5]
	v_readlane_b32 s4, v254, 25
	v_readlane_b32 s5, v254, 26
	v_mov_b32_e32 v4, v182
	s_andn2_b64 vcc, exec, s[4:5]
	s_barrier
	s_cbranch_vccnz .LBB0_1706
	v_and_b32_e32 v101, 64, v4
	v_and_b32_e32 v100, 15, v4
	v_ashrrev_i32_e32 v5, 1, v4
	v_lshrrev_b32_e32 v4, 2, v4
	s_load_dwordx2 s[4:5], s[0:1], 0xf8
	v_and_b32_e32 v4, 12, v4
	s_movk_i32 s6, 0xffc0
	v_and_or_b32 v106, v5, s6, v4
	s_load_dwordx2 s[6:7], s[0:1], 0x130
	v_readlane_b32 s10, v254, 51
	s_mul_i32 s9, s10, 0x900000
	s_mul_hi_u32 s8, s10, 0x900000
	s_waitcnt lgkmcnt(0)
	s_add_u32 s14, s4, s9
	s_addc_u32 s15, s5, s8
	v_readlane_b32 s16, v254, 18
	v_readlane_b32 s98, v254, 16
	v_readlane_b32 s99, v254, 17
	v_readlane_b32 s100, v254, 0
	v_readlane_b32 s101, v254, 51
	s_nop 1
	s_and_b32 s100, s100, 7
	s_lshl_b32 s100, s100, 8
	s_lshl_b32 s101, s101, 2
	s_add_u32 s100, s100, s101
	s_add_u32 s100, s100, 0x100
	s_add_u32 s98, s98, s100
	s_addc_u32 s99, s99, 0
	v_readlane_b32 s11, v254, 52
	s_branch .LBB0_1700
.LBB0_1699:
	s_or_b64 exec, exec, s[8:9]
	v_lshrrev_b32_e32 v253, 6, v182
	s_nop 0
	v_readfirstlane_b32 s8, v253
	s_nop 0
	s_cmp_lg_u32 s8, 0
	s_cbranch_scc1 .Ldyn2_wait
	s_mov_b64 s[8:9], exec
	s_mov_b64 exec, 1
	s_nop 1
	v_mov_b32_e32 v252, 1
	global_atomic_add v253, v164, v252, s[98:99] sc0
	v_mov_b32_e32 v251, 0x11ff0
	s_waitcnt vmcnt(0)
	ds_write_b32 v251, v253
	s_mov_b64 exec, s[8:9]
.Ldyn2_wait:
	s_waitcnt lgkmcnt(0)
	s_barrier
	v_mov_b32_e32 v251, 0x11ff0
	ds_read_b32 v253, v251
	s_waitcnt lgkmcnt(0)
	v_readfirstlane_b32 s16, v253
	s_nop 0
	s_add_i32 s16, s16, 64
	s_cmpk_lt_u32 s16, 0x288
	s_cbranch_scc0 .LBB0_1706
